# attention priority = 2*(MFMA segment) + token half (s_setprio follows the segment, per half)
# baseline (speedup 1.0000x reference)
.LBB0_305:
	v_lshl_add_u64 v[4:5], s[6:7], 0, v[178:179]
	v_mov_b64_e32 v[6:7], s[82:83]
	v_mad_u64_u32 v[8:9], s[8:9], v4, s85, v[6:7]
	v_mov_b32_e32 v4, v9
	s_lshl_b32 s11, s11, 6
	v_mad_u64_u32 v[4:5], s[8:9], v5, s85, v[4:5]
	v_mov_b32_e32 v9, v4
	s_lshl_b32 s80, s11, 1
	v_lshl_add_u64 v[4:5], v[8:9], 0, s[80:81]
	v_lshl_add_u64 v[4:5], v[4:5], 0, v[0:1]
	global_load_dwordx4 v[162:165], v[4:5], off offset:1024
	global_load_dwordx4 v[166:169], v[4:5], off offset:1280
	v_lshl_add_u64 v[4:5], s[6:7], 0, v[180:181]
	v_mad_u64_u32 v[6:7], s[6:7], v4, s85, v[6:7]
	v_mov_b32_e32 v4, v7
	v_mad_u64_u32 v[4:5], s[6:7], v5, s85, v[4:5]
	v_mov_b32_e32 v7, v4
	v_lshl_add_u64 v[4:5], v[6:7], 0, s[80:81]
	v_lshl_add_u64 v[4:5], v[4:5], 0, v[0:1]
	global_load_dwordx4 v[170:173], v[4:5], off offset:1024
	global_load_dwordx4 v[174:177], v[4:5], off offset:1280
	s_lshl_b32 s20, s10, 6
	s_add_i32 s24, s22, 0xffffff80
	s_add_i32 s25, s22, 0xbf
	s_add_i32 s26, s22, 0xffffffbf
	s_add_i32 s27, s22, 0x41
	v_lshlrev_b32_e32 v200, 3, v3
	v_mul_f32_e32 v186, 0x3fb8aa3b, v2
	v_lshlrev_b32_e32 v2, 2, v3
	v_lshrrev_b32_e32 v3, 2, v187
	s_add_u32 s6, s82, s80
	v_and_b32_e32 v183, 63, v187
	v_and_or_b32 v202, v3, 3, v2
	v_lshlrev_b32_e32 v3, 2, v187
	v_sub_u32_e32 v2, v2, v189
	s_addc_u32 s7, s83, 0
	v_mov_b32_e32 v14, v1
	v_mov_b32_e32 v15, v1
	v_cmp_gt_u32_e32 vcc, 32, v183
	v_and_b32_e32 v16, 16, v187
	v_and_b32_e32 v17, 12, v3
	v_add_u32_e32 v203, 0x80, v2
	v_lshl_add_u64 v[184:185], s[6:7], 0, v[0:1]
	v_mov_b32_e32 v0, v1
	v_mov_b32_e32 v2, v1
	v_mov_b32_e32 v3, v1
	v_mov_b32_e32 v4, v1
	v_mov_b32_e32 v5, v1
	v_mov_b32_e32 v6, v1
	v_mov_b32_e32 v7, v1
	v_mov_b32_e32 v8, v1
	v_mov_b32_e32 v9, v1
	v_mov_b32_e32 v10, v1
	v_mov_b32_e32 v11, v1
	v_mov_b32_e32 v12, v1
	v_mov_b32_e32 v13, v1
	v_mov_b64_e32 v[64:65], v[14:15]
	v_mov_b64_e32 v[32:33], v[14:15]
	v_mov_b64_e32 v[48:49], v[14:15]
	v_cndmask_b32_e64 v201, 0, 1.0, vcc
	v_lshlrev_b32_e32 v204, 1, v16
	v_lshlrev_b32_e32 v205, 1, v17
	v_mov_b64_e32 v[62:63], v[12:13]
	v_mov_b64_e32 v[60:61], v[10:11]
	v_mov_b64_e32 v[58:59], v[8:9]
	v_mov_b64_e32 v[56:57], v[6:7]
	v_mov_b64_e32 v[54:55], v[4:5]
	v_mov_b64_e32 v[52:53], v[2:3]
	v_mov_b64_e32 v[50:51], v[0:1]
	v_mov_b64_e32 v[30:31], v[12:13]
	v_mov_b64_e32 v[28:29], v[10:11]
	v_mov_b64_e32 v[26:27], v[8:9]
	v_mov_b64_e32 v[24:25], v[6:7]
	v_mov_b64_e32 v[22:23], v[4:5]
	v_mov_b64_e32 v[20:21], v[2:3]
	v_mov_b64_e32 v[18:19], v[0:1]
	v_mov_b64_e32 v[46:47], v[12:13]
	v_mov_b64_e32 v[44:45], v[10:11]
	v_mov_b64_e32 v[42:43], v[8:9]
	v_mov_b64_e32 v[40:41], v[6:7]
	v_mov_b64_e32 v[38:39], v[4:5]
	v_mov_b64_e32 v[36:37], v[2:3]
	v_mov_b64_e32 v[34:35], v[0:1]
	v_mov_b64_e32 v[16:17], v[14:15]
	s_mov_b32 s28, 0
	v_mov_b32_e32 v199, v201
	v_mov_b32_e32 v188, v186
	v_mov_b64_e32 v[14:15], v[12:13]
	v_mov_b64_e32 v[12:13], v[10:11]
	v_mov_b64_e32 v[10:11], v[8:9]
	v_mov_b64_e32 v[8:9], v[6:7]
	v_mov_b64_e32 v[6:7], v[4:5]
	v_mov_b64_e32 v[4:5], v[2:3]
	v_mov_b64_e32 v[2:3], v[0:1]
	s_waitcnt lgkmcnt(0)
	s_barrier
	v_readfirstlane_b32 s99, v244
	s_lshr_b32 s99, s99, 8
	s_cmp_eq_u32 s99, 0
	s_cbranch_scc1 .Lpr_mix2e_0
	s_setprio 1
	s_branch .Lpr_mix2e_1
.Lpr_mix2e_0:
	s_setprio 0
.Lpr_mix2e_1:
.LBB0_306:
	s_cmp_lt_i32 s21, 5
	s_cselect_b64 s[6:7], -1, 0
	s_cmp_gt_i32 s21, 4
	s_cselect_b64 s[8:9], -1, 0
	s_mov_b32 s29, 5
	s_and_b64 vcc, exec, s[8:9]
	s_mov_b32 s12, s21
	s_cbranch_vccz .LBB0_308
	s_branch .LBB0_310

.LBB0_319:
	v_or_b32_e32 v221, s31, v202
	v_mad_u32_u24 v225, v221, s89, v206
	ds_read_b64_tr_b16 v[226:227], v225 offset:18432
	ds_read_b64_tr_b16 v[228:229], v225 offset:19584
	ds_read_b64_tr_b16 v[230:231], v225 offset:18496
	ds_read_b64_tr_b16 v[232:233], v225 offset:19648
	ds_read_b64_tr_b16 v[234:235], v225 offset:20736
	ds_read_b64_tr_b16 v[236:237], v225 offset:21888
	v_pk_add_f32 v[114:115], v[114:115], v[186:187] op_sel_hi:[1,0] neg_lo:[0,1] neg_hi:[0,1]
	v_pk_add_f32 v[116:117], v[116:117], v[186:187] op_sel_hi:[1,0] neg_lo:[0,1] neg_hi:[0,1]
	v_exp_f32_e32 v190, v114
	v_exp_f32_e32 v191, v115
	v_exp_f32_e32 v192, v116
	v_exp_f32_e32 v193, v117
	v_pk_add_f32 v[116:117], v[118:119], v[186:187] op_sel_hi:[1,0] neg_lo:[0,1] neg_hi:[0,1]
	v_pk_add_f32 v[114:115], v[190:191], 0 op_sel_hi:[1,0]
	v_exp_f32_e32 v194, v116
	v_exp_f32_e32 v195, v117
	v_pk_add_f32 v[116:117], v[120:121], v[186:187] op_sel_hi:[1,0] neg_lo:[0,1] neg_hi:[0,1]
	v_pk_add_f32 v[114:115], v[192:193], v[114:115]
	v_exp_f32_e32 v196, v116
	v_exp_f32_e32 v197, v117
	v_pk_add_f32 v[116:117], v[122:123], v[186:187] op_sel_hi:[1,0] neg_lo:[0,1] neg_hi:[0,1]
	v_pk_add_f32 v[114:115], v[194:195], v[114:115]
	v_exp_f32_e32 v122, v116
	v_exp_f32_e32 v123, v117
	v_pk_add_f32 v[116:117], v[124:125], v[186:187] op_sel_hi:[1,0] neg_lo:[0,1] neg_hi:[0,1]
	v_pk_add_f32 v[114:115], v[196:197], v[114:115]
	v_exp_f32_e32 v124, v116
	v_exp_f32_e32 v125, v117
	v_pk_add_f32 v[116:117], v[126:127], v[186:187] op_sel_hi:[1,0] neg_lo:[0,1] neg_hi:[0,1]
	v_pk_add_f32 v[114:115], v[122:123], v[114:115]
	v_exp_f32_e32 v126, v116
	v_exp_f32_e32 v127, v117
	v_pk_add_f32 v[116:117], v[128:129], v[186:187] op_sel_hi:[1,0] neg_lo:[0,1] neg_hi:[0,1]
	v_pk_add_f32 v[114:115], v[124:125], v[114:115]
	v_exp_f32_e32 v128, v116
	v_exp_f32_e32 v129, v117
	v_pk_add_f32 v[114:115], v[126:127], v[114:115]
	v_pk_add_f32 v[98:99], v[98:99], v[186:187] op_sel_hi:[1,0] neg_lo:[0,1] neg_hi:[0,1]
	v_pk_add_f32 v[100:101], v[100:101], v[186:187] op_sel_hi:[1,0] neg_lo:[0,1] neg_hi:[0,1]
	v_pk_add_f32 v[116:117], v[128:129], v[114:115]
	v_exp_f32_e32 v114, v98
	v_exp_f32_e32 v115, v99
	v_pk_add_f32 v[82:83], v[82:83], v[188:189] op_sel_hi:[1,0] neg_lo:[0,1] neg_hi:[0,1]
	v_pk_add_f32 v[84:85], v[84:85], v[188:189] op_sel_hi:[1,0] neg_lo:[0,1] neg_hi:[0,1]
	v_pk_add_f32 v[66:67], v[66:67], v[188:189] op_sel_hi:[1,0] neg_lo:[0,1] neg_hi:[0,1]
	v_pk_add_f32 v[98:99], v[114:115], v[116:117]
	v_exp_f32_e32 v116, v100
	v_exp_f32_e32 v117, v101
	v_pk_add_f32 v[100:101], v[102:103], v[186:187] op_sel_hi:[1,0] neg_lo:[0,1] neg_hi:[0,1]
	v_pk_add_f32 v[68:69], v[68:69], v[188:189] op_sel_hi:[1,0] neg_lo:[0,1] neg_hi:[0,1]
	v_exp_f32_e32 v118, v100
	v_exp_f32_e32 v119, v101
	v_pk_add_f32 v[100:101], v[104:105], v[186:187] op_sel_hi:[1,0] neg_lo:[0,1] neg_hi:[0,1]
	v_pk_add_f32 v[98:99], v[116:117], v[98:99]
	v_exp_f32_e32 v120, v100
	v_exp_f32_e32 v121, v101
	v_pk_add_f32 v[98:99], v[118:119], v[98:99]
	v_or_b32_e32 v207, s31, v202
	v_pk_add_f32 v[100:101], v[120:121], v[98:99]
	v_pk_add_f32 v[98:99], v[106:107], v[186:187] op_sel_hi:[1,0] neg_lo:[0,1] neg_hi:[0,1]
	s_nop 0
	v_exp_f32_e32 v98, v98
	v_exp_f32_e32 v99, v99
	s_nop 0
	v_pk_add_f32 v[102:103], v[98:99], v[100:101]
	v_pk_add_f32 v[100:101], v[108:109], v[186:187] op_sel_hi:[1,0] neg_lo:[0,1] neg_hi:[0,1]
	v_exp_f32_e32 v108, v84
	v_exp_f32_e32 v100, v100
	v_exp_f32_e32 v101, v101
	v_exp_f32_e32 v109, v85
	v_pk_add_f32 v[84:85], v[86:87], v[188:189] op_sel_hi:[1,0] neg_lo:[0,1] neg_hi:[0,1]
	v_pk_add_f32 v[104:105], v[100:101], v[102:103]
	v_pk_add_f32 v[102:103], v[110:111], v[186:187] op_sel_hi:[1,0] neg_lo:[0,1] neg_hi:[0,1]
	v_exp_f32_e32 v110, v84
	v_exp_f32_e32 v102, v102
	v_exp_f32_e32 v103, v103
	v_exp_f32_e32 v111, v85
	v_pk_add_f32 v[84:85], v[88:89], v[188:189] op_sel_hi:[1,0] neg_lo:[0,1] neg_hi:[0,1]
	v_pk_add_f32 v[106:107], v[102:103], v[104:105]
	v_pk_add_f32 v[104:105], v[112:113], v[186:187] op_sel_hi:[1,0] neg_lo:[0,1] neg_hi:[0,1]
	v_exp_f32_e32 v112, v84
	v_exp_f32_e32 v104, v104
	v_exp_f32_e32 v105, v105
	v_exp_f32_e32 v113, v85
	v_pk_add_f32 v[84:85], v[90:91], v[188:189] op_sel_hi:[1,0] neg_lo:[0,1] neg_hi:[0,1]
	v_pk_add_f32 v[106:107], v[104:105], v[106:107]
	s_nop 0
	v_add_f32_e32 v106, v106, v107
	v_add_f32_e32 v201, v201, v106
	v_exp_f32_e32 v106, v82
	v_exp_f32_e32 v107, v83
	v_exp_f32_e32 v90, v84
	v_exp_f32_e32 v91, v85
	v_pk_add_f32 v[84:85], v[92:93], v[188:189] op_sel_hi:[1,0] neg_lo:[0,1] neg_hi:[0,1]
	v_pk_add_f32 v[82:83], v[106:107], 0 op_sel_hi:[1,0]
	v_exp_f32_e32 v92, v84
	v_pk_add_f32 v[82:83], v[108:109], v[82:83]
	v_exp_f32_e32 v93, v85
	v_pk_add_f32 v[84:85], v[94:95], v[188:189] op_sel_hi:[1,0] neg_lo:[0,1] neg_hi:[0,1]
	v_pk_add_f32 v[82:83], v[110:111], v[82:83]
	v_exp_f32_e32 v94, v84
	v_exp_f32_e32 v95, v85
	v_pk_add_f32 v[84:85], v[96:97], v[188:189] op_sel_hi:[1,0] neg_lo:[0,1] neg_hi:[0,1]
	v_pk_add_f32 v[82:83], v[112:113], v[82:83]
	v_exp_f32_e32 v96, v84
	v_exp_f32_e32 v97, v85
	v_pk_add_f32 v[82:83], v[90:91], v[82:83]
	s_nop 0
	v_pk_add_f32 v[82:83], v[92:93], v[82:83]
	s_nop 0
	v_pk_add_f32 v[82:83], v[94:95], v[82:83]
	s_nop 0
	v_pk_add_f32 v[84:85], v[96:97], v[82:83]
	v_exp_f32_e32 v82, v66
	v_exp_f32_e32 v83, v67
	s_nop 0
	v_pk_add_f32 v[66:67], v[82:83], v[84:85]
	v_exp_f32_e32 v84, v68
	v_exp_f32_e32 v85, v69
	v_pk_add_f32 v[68:69], v[70:71], v[188:189] op_sel_hi:[1,0] neg_lo:[0,1] neg_hi:[0,1]
	v_pk_add_f32 v[66:67], v[84:85], v[66:67]
	v_exp_f32_e32 v86, v68
	v_exp_f32_e32 v87, v69
	v_pk_add_f32 v[68:69], v[72:73], v[188:189] op_sel_hi:[1,0] neg_lo:[0,1] neg_hi:[0,1]
	v_pk_add_f32 v[66:67], v[86:87], v[66:67]
	v_exp_f32_e32 v88, v68
	v_exp_f32_e32 v89, v69
	s_nop 0
	v_pk_add_f32 v[68:69], v[88:89], v[66:67]
	v_pk_add_f32 v[66:67], v[74:75], v[188:189] op_sel_hi:[1,0] neg_lo:[0,1] neg_hi:[0,1]
	s_nop 0
	v_exp_f32_e32 v66, v66
	v_exp_f32_e32 v67, v67
	s_nop 0
	v_pk_add_f32 v[70:71], v[66:67], v[68:69]
	v_pk_add_f32 v[68:69], v[76:77], v[188:189] op_sel_hi:[1,0] neg_lo:[0,1] neg_hi:[0,1]
	s_nop 0
	v_exp_f32_e32 v68, v68
	v_exp_f32_e32 v69, v69
	s_nop 0
	v_pk_add_f32 v[72:73], v[68:69], v[70:71]
	v_pk_add_f32 v[70:71], v[78:79], v[188:189] op_sel_hi:[1,0] neg_lo:[0,1] neg_hi:[0,1]
	s_nop 0
	v_exp_f32_e32 v70, v70
	v_exp_f32_e32 v71, v71
	s_nop 0
	v_pk_add_f32 v[74:75], v[70:71], v[72:73]
	v_pk_add_f32 v[72:73], v[80:81], v[188:189] op_sel_hi:[1,0] neg_lo:[0,1] neg_hi:[0,1]
	s_nop 0
	v_exp_f32_e32 v72, v72
	v_exp_f32_e32 v73, v73
	s_nop 0
	v_pk_add_f32 v[74:75], v[72:73], v[74:75]
	s_nop 0
	v_add_f32_e32 v74, v74, v75
	v_add_f32_e32 v199, v199, v74
	v_cvt_pk_bf16_f32 v74, v190, v191
	v_cvt_pk_bf16_f32 v75, v192, v193
	v_cvt_pk_bf16_f32 v76, v194, v195
	v_cvt_pk_bf16_f32 v77, v196, v197
	v_cvt_pk_bf16_f32 v78, v106, v107
	v_cvt_pk_bf16_f32 v79, v108, v109
	v_cvt_pk_bf16_f32 v80, v110, v111
	v_cvt_pk_bf16_f32 v81, v112, v113
	s_cmp_eq_u32 s99, 0
	s_cbranch_scc1 .Lpr_mix2a_0
	s_setprio 3
	s_branch .Lpr_mix2a_1
.Lpr_mix2a_0:
	s_setprio 2
.Lpr_mix2a_1:
	s_waitcnt lgkmcnt(4)
	v_mfma_f32_32x32x16_bf16 v[50:65], v[226:229], v[74:77], v[50:65]
	v_mfma_f32_32x32x16_bf16 v[18:33], v[226:229], v[78:81], v[18:33]
	ds_read_b64_tr_b16 v[226:227], v225 offset:20800
	ds_read_b64_tr_b16 v[228:229], v225 offset:21952
	s_waitcnt lgkmcnt(4)
	v_mfma_f32_32x32x16_bf16 v[34:49], v[230:233], v[74:77], v[34:49]
	v_cvt_pk_bf16_f32 v74, v122, v123
	v_cvt_pk_bf16_f32 v75, v124, v125
	v_cvt_pk_bf16_f32 v76, v126, v127
	v_cvt_pk_bf16_f32 v77, v128, v129
	v_mfma_f32_32x32x16_bf16 v[2:17], v[230:233], v[78:81], v[2:17]
	v_cvt_pk_bf16_f32 v78, v90, v91
	v_cvt_pk_bf16_f32 v79, v92, v93
	v_cvt_pk_bf16_f32 v80, v94, v95
	v_cvt_pk_bf16_f32 v81, v96, v97
	ds_read_b64_tr_b16 v[230:231], v225 offset:23040
	ds_read_b64_tr_b16 v[232:233], v225 offset:24192
	s_waitcnt lgkmcnt(4)
	v_mfma_f32_32x32x16_bf16 v[50:65], v[234:237], v[74:77], v[50:65]
	v_mfma_f32_32x32x16_bf16 v[18:33], v[234:237], v[78:81], v[18:33]
	ds_read_b64_tr_b16 v[234:235], v225 offset:23104
	ds_read_b64_tr_b16 v[236:237], v225 offset:24256
	s_waitcnt lgkmcnt(4)
	v_mfma_f32_32x32x16_bf16 v[34:49], v[226:229], v[74:77], v[34:49]
	v_cvt_pk_bf16_f32 v74, v114, v115
	v_cvt_pk_bf16_f32 v75, v116, v117
	v_cvt_pk_bf16_f32 v76, v118, v119
	v_cvt_pk_bf16_f32 v77, v120, v121
	v_mfma_f32_32x32x16_bf16 v[2:17], v[226:229], v[78:81], v[2:17]
	v_cvt_pk_bf16_f32 v78, v82, v83
	v_cvt_pk_bf16_f32 v79, v84, v85
	v_cvt_pk_bf16_f32 v80, v86, v87
	v_cvt_pk_bf16_f32 v81, v88, v89
	ds_read_b64_tr_b16 v[226:227], v225 offset:25344
	ds_read_b64_tr_b16 v[228:229], v225 offset:26496
	s_waitcnt lgkmcnt(4)
	v_mfma_f32_32x32x16_bf16 v[50:65], v[230:233], v[74:77], v[50:65]
	v_mfma_f32_32x32x16_bf16 v[18:33], v[230:233], v[78:81], v[18:33]
	ds_read_b64_tr_b16 v[230:231], v225 offset:25408
	ds_read_b64_tr_b16 v[232:233], v225 offset:26560
	s_waitcnt lgkmcnt(4)
	v_mfma_f32_32x32x16_bf16 v[34:49], v[234:237], v[74:77], v[34:49]
	v_cvt_pk_bf16_f32 v74, v98, v99
	v_cvt_pk_bf16_f32 v75, v100, v101
	v_cvt_pk_bf16_f32 v76, v102, v103
	v_cvt_pk_bf16_f32 v77, v104, v105
	v_mfma_f32_32x32x16_bf16 v[2:17], v[234:237], v[78:81], v[2:17]
	v_cvt_pk_bf16_f32 v66, v66, v67
	v_cvt_pk_bf16_f32 v67, v68, v69
	v_cvt_pk_bf16_f32 v68, v70, v71
	v_cvt_pk_bf16_f32 v69, v72, v73
	s_waitcnt lgkmcnt(2)
	v_mfma_f32_32x32x16_bf16 v[50:65], v[226:229], v[74:77], v[50:65]
	v_mfma_f32_32x32x16_bf16 v[18:33], v[226:229], v[66:69], v[18:33]
	s_waitcnt lgkmcnt(0)
	v_mfma_f32_32x32x16_bf16 v[34:49], v[230:233], v[74:77], v[34:49]
	v_mfma_f32_32x32x16_bf16 v[2:17], v[230:233], v[66:69], v[2:17]
	s_cmp_eq_u32 s99, 0
	s_cbranch_scc1 .Lpr_mix2b_0
	s_setprio 1
	s_branch .Lpr_mix2b_1

.Lpr_mix2b_1:
.LBB0_320:
	s_xor_b64 s[6:7], s[14:15], -1
	s_mov_b32 s31, 64
	s_mov_b64 s[14:15], 0
	s_and_b64 vcc, exec, s[6:7]
	s_cbranch_vccnz .LBB0_332

.LBB0_323:
	s_andn2_b64 vcc, exec, s[6:7]
	s_cbranch_vccnz .LBB0_320
	v_or_b32_e32 v66, s31, v189
	v_mad_u32_u24 v207, v66, s89, v0
	s_cmp_eq_u32 s99, 0
	s_cbranch_scc1 .Lpr_mix2q_0
	s_setprio 3
	s_branch .Lpr_mix2q_1

.Lpr_mix2q_1:
	ds_read_b128 v[66:69], v207
	ds_read_b128 v[70:73], v207 offset:32
	ds_read_b128 v[74:77], v207 offset:64
	ds_read_b128 v[78:81], v207 offset:96
	s_cmp_lt_i32 s34, s26
	s_cselect_b64 s[6:7], -1, 0
	s_waitcnt vmcnt(11) lgkmcnt(3)
	v_mfma_f32_32x32x16_bf16 v[114:129], v[66:69], v[130:133], 0
	s_cmp_gt_i32 s34, s27
	s_cselect_b64 s[36:37], -1, 0
	s_or_b64 s[6:7], s[6:7], s[36:37]
	s_waitcnt vmcnt(7)
	v_mfma_f32_32x32x16_bf16 v[82:97], v[66:69], v[146:149], 0
	ds_read_b128 v[66:69], v207 offset:4608
	ds_read_b128 v[190:193], v207 offset:4640
	ds_read_b128 v[194:197], v207 offset:4672
	ds_read_b128 v[208:211], v207 offset:4704
	s_waitcnt lgkmcnt(6)
	v_mfma_f32_32x32x16_bf16 v[114:129], v[70:73], v[134:137], v[114:129]
	s_waitcnt vmcnt(6)
	v_mfma_f32_32x32x16_bf16 v[82:97], v[70:73], v[150:153], v[82:97]
	s_waitcnt lgkmcnt(5)
	v_mfma_f32_32x32x16_bf16 v[114:129], v[74:77], v[138:141], v[114:129]
	s_waitcnt vmcnt(5)
	v_mfma_f32_32x32x16_bf16 v[82:97], v[74:77], v[154:157], v[82:97]
	s_waitcnt lgkmcnt(4)
	v_mfma_f32_32x32x16_bf16 v[114:129], v[78:81], v[142:145], v[114:129]
	s_waitcnt vmcnt(4)
	v_mfma_f32_32x32x16_bf16 v[82:97], v[78:81], v[158:161], v[82:97]
	s_waitcnt lgkmcnt(3)
	v_mfma_f32_32x32x16_bf16 v[98:113], v[66:69], v[130:133], 0
	v_mfma_f32_32x32x16_bf16 v[66:81], v[66:69], v[146:149], 0
	s_waitcnt lgkmcnt(2)
	v_mfma_f32_32x32x16_bf16 v[98:113], v[190:193], v[134:137], v[98:113]
	v_mfma_f32_32x32x16_bf16 v[66:81], v[190:193], v[150:153], v[66:81]
	v_add_u32_e32 v190, s34, v203
	s_and_b64 s[34:35], s[10:11], s[6:7]
	v_cndmask_b32_e64 v191, 0, 1, s[34:35]
	v_cmp_ne_u32_e64 s[6:7], 1, v191
	s_andn2_b64 vcc, exec, s[34:35]
	v_subrev_u32_e32 v190, s22, v190
	s_waitcnt lgkmcnt(1)
	v_mfma_f32_32x32x16_bf16 v[98:113], v[194:197], v[138:141], v[98:113]
	v_mfma_f32_32x32x16_bf16 v[66:81], v[194:197], v[154:157], v[66:81]
	s_waitcnt lgkmcnt(0)
	v_mfma_f32_32x32x16_bf16 v[98:113], v[208:211], v[142:145], v[98:113]
	v_mfma_f32_32x32x16_bf16 v[66:81], v[208:211], v[158:161], v[66:81]
	s_cmp_eq_u32 s99, 0
	s_cbranch_scc1 .Lpr_mix2r_0
	s_setprio 1
	s_branch .Lpr_mix2r_1

.Lpr_mix2r_1:
	s_cbranch_vccnz .LBB0_326
	v_cmp_gt_u32_e32 vcc, s33, v190
	v_add_u32_e32 v191, 0xffffff00, v190
	s_nop 0
	v_cndmask_b32_e32 v114, v243, v114, vcc
	v_cmp_lt_u32_e32 vcc, s67, v191
	v_add_u32_e32 v191, 0xffffff01, v190
	s_nop 0
	v_cndmask_b32_e32 v115, v243, v115, vcc
	v_cmp_lt_u32_e32 vcc, s67, v191
	v_add_u32_e32 v191, 0xffffff02, v190
	s_nop 0
	v_cndmask_b32_e32 v116, v243, v116, vcc
	v_cmp_lt_u32_e32 vcc, s67, v191
	v_add_u32_e32 v191, 0xffffff07, v190
	s_nop 0
	v_cndmask_b32_e32 v117, v243, v117, vcc
	v_cmp_lt_u32_e32 vcc, s67, v191
	v_add_u32_e32 v191, 0xffffff08, v190
	s_nop 0
	v_cndmask_b32_e32 v118, v243, v118, vcc
	v_cmp_lt_u32_e32 vcc, s67, v191
	v_add_u32_e32 v191, 0xffffff09, v190
	s_nop 0
	v_cndmask_b32_e32 v119, v243, v119, vcc
	v_cmp_lt_u32_e32 vcc, s67, v191
	v_add_u32_e32 v191, 0xffffff0a, v190
	s_nop 0
	v_cndmask_b32_e32 v120, v243, v120, vcc
	v_cmp_lt_u32_e32 vcc, s67, v191
	v_add_u32_e32 v191, 0xffffff0f, v190
	s_nop 0
	v_cndmask_b32_e32 v121, v243, v121, vcc
	v_cmp_lt_u32_e32 vcc, s67, v191
	v_add_u32_e32 v191, 0xffffff10, v190
	s_nop 0
	v_cndmask_b32_e32 v122, v243, v122, vcc
	v_cmp_lt_u32_e32 vcc, s67, v191
	v_add_u32_e32 v191, 0xffffff11, v190
	s_nop 0
	v_cndmask_b32_e32 v123, v243, v123, vcc
	v_cmp_lt_u32_e32 vcc, s67, v191
	v_add_u32_e32 v191, 0xffffff12, v190
	s_nop 0
	v_cndmask_b32_e32 v124, v243, v124, vcc
	v_cmp_lt_u32_e32 vcc, s67, v191
	v_add_u32_e32 v191, 0xffffff17, v190
	s_nop 0
	v_cndmask_b32_e32 v125, v243, v125, vcc
	v_cmp_lt_u32_e32 vcc, s67, v191
	v_add_u32_e32 v191, 0xffffff18, v190
	s_nop 0
	v_cndmask_b32_e32 v126, v243, v126, vcc
	v_cmp_lt_u32_e32 vcc, s67, v191
	v_add_u32_e32 v191, 0xffffff19, v190
	s_nop 0
	v_cndmask_b32_e32 v127, v243, v127, vcc
	v_cmp_lt_u32_e32 vcc, s67, v191
	v_add_u32_e32 v191, 0xffffff1a, v190
	s_nop 0
	v_cndmask_b32_e32 v128, v243, v128, vcc
	v_cmp_lt_u32_e32 vcc, s67, v191
	v_add_u32_e32 v191, 0xffffff1f, v190
	s_nop 0
	v_cndmask_b32_e32 v129, v243, v129, vcc
	v_cmp_lt_u32_e32 vcc, s67, v191
	v_add_u32_e32 v191, 0xffffff20, v190
	s_nop 0
	v_cndmask_b32_e32 v98, v243, v98, vcc
	v_cmp_lt_u32_e32 vcc, s67, v191
	v_add_u32_e32 v191, 0xffffff21, v190
	s_nop 0
	v_cndmask_b32_e32 v99, v243, v99, vcc
	v_cmp_lt_u32_e32 vcc, s67, v191
	v_add_u32_e32 v191, 0xffffff22, v190
	s_nop 0
	v_cndmask_b32_e32 v100, v243, v100, vcc
	v_cmp_lt_u32_e32 vcc, s67, v191
	v_add_u32_e32 v191, 0xffffff27, v190
	s_nop 0
	v_cndmask_b32_e32 v101, v243, v101, vcc
	v_cmp_lt_u32_e32 vcc, s67, v191
	v_add_u32_e32 v191, 0xffffff28, v190
	s_nop 0
	v_cndmask_b32_e32 v102, v243, v102, vcc
	v_cmp_lt_u32_e32 vcc, s67, v191
	v_add_u32_e32 v191, 0xffffff29, v190
	s_nop 0
	v_cndmask_b32_e32 v103, v243, v103, vcc
	v_cmp_lt_u32_e32 vcc, s67, v191
	v_add_u32_e32 v191, 0xffffff2a, v190
	s_nop 0
	v_cndmask_b32_e32 v104, v243, v104, vcc
	v_cmp_lt_u32_e32 vcc, s67, v191
	v_add_u32_e32 v191, 0xffffff2f, v190
	s_nop 0
	v_cndmask_b32_e32 v105, v243, v105, vcc
	v_cmp_lt_u32_e32 vcc, s67, v191
	v_add_u32_e32 v191, 0xffffff30, v190
	s_nop 0
	v_cndmask_b32_e32 v106, v243, v106, vcc
	v_cmp_lt_u32_e32 vcc, s67, v191
	v_add_u32_e32 v191, 0xffffff31, v190
	s_nop 0
	v_cndmask_b32_e32 v107, v243, v107, vcc
	v_cmp_lt_u32_e32 vcc, s67, v191
	v_add_u32_e32 v191, 0xffffff32, v190
	s_nop 0
	v_cndmask_b32_e32 v108, v243, v108, vcc
	v_cmp_lt_u32_e32 vcc, s67, v191
	v_add_u32_e32 v191, 0xffffff37, v190
	s_nop 0
	v_cndmask_b32_e32 v109, v243, v109, vcc
	v_cmp_lt_u32_e32 vcc, s67, v191
	v_add_u32_e32 v191, 0xffffff38, v190
	s_nop 0
	v_cndmask_b32_e32 v110, v243, v110, vcc
	v_cmp_lt_u32_e32 vcc, s67, v191
	v_add_u32_e32 v191, 0xffffff39, v190
	s_nop 0
	v_cndmask_b32_e32 v111, v243, v111, vcc
	v_cmp_lt_u32_e32 vcc, s67, v191
	v_add_u32_e32 v191, 0xffffff3a, v190
	s_nop 0
	v_cndmask_b32_e32 v112, v243, v112, vcc
	v_cmp_lt_u32_e32 vcc, s67, v191
	s_nop 1
	v_cndmask_b32_e32 v113, v243, v113, vcc

.LBB0_358:
	v_and_b32_e32 v197, 63, v201
	s_lshl_b32 s44, s18, 6
	v_cmp_gt_u32_e32 vcc, 32, v197
	v_lshlrev_b32_e32 v214, 3, v3
	s_cmp_gt_u32 s20, 4
	v_cndmask_b32_e64 v212, 0, 1.0, vcc
	s_waitcnt lgkmcnt(0)
	s_barrier
	s_cbranch_scc1 .LBB0_393
	v_writelane_b32 v255, s48, 0
	v_mul_f32_e32 v200, 0x3fb8aa3b, v2
	s_add_i32 s46, s45, 0xffffff80
	v_writelane_b32 v255, s49, 1
	s_add_i32 s47, s45, 0xbf
	s_add_i32 s48, s45, 0xffffffbf
	s_add_i32 s49, s45, 0x41
	v_lshlrev_b32_e32 v2, 2, v3
	v_lshrrev_b32_e32 v3, 2, v201
	s_lshl_b32 s6, s24, 1
	v_and_or_b32 v215, v3, 3, v2
	v_lshlrev_b32_e32 v3, 2, v201
	s_add_u32 s6, s82, s6
	v_and_b32_e32 v16, 16, v201
	v_and_b32_e32 v17, 12, v3
	v_sub_u32_e32 v2, v2, v203
	s_addc_u32 s7, s83, 0
	v_mov_b32_e32 v14, v1
	v_mov_b32_e32 v15, v1
	v_add_u32_e32 v217, 0x80, v2
	v_lshl_add_u64 v[198:199], s[6:7], 0, v[0:1]
	v_mov_b32_e32 v0, v1
	v_mov_b32_e32 v2, v1
	v_mov_b32_e32 v3, v1
	v_mov_b32_e32 v4, v1
	v_mov_b32_e32 v5, v1
	v_mov_b32_e32 v6, v1
	v_mov_b32_e32 v7, v1
	v_mov_b32_e32 v8, v1
	v_mov_b32_e32 v9, v1
	v_mov_b32_e32 v10, v1
	v_mov_b32_e32 v11, v1
	v_mov_b32_e32 v12, v1
	v_mov_b32_e32 v13, v1
	v_lshlrev_b32_e32 v222, 1, v16
	v_lshlrev_b32_e32 v223, 1, v17
	v_mov_b64_e32 v[78:79], v[14:15]
	v_mov_b64_e32 v[46:47], v[14:15]
	v_mov_b64_e32 v[62:63], v[14:15]
	v_mov_b64_e32 v[30:31], v[14:15]
	s_mov_b32 s61, 0
	v_mov_b32_e32 v216, v212
	v_mov_b32_e32 v202, v200
	v_mov_b64_e32 v[76:77], v[12:13]
	v_mov_b64_e32 v[74:75], v[10:11]
	v_mov_b64_e32 v[72:73], v[8:9]
	v_mov_b64_e32 v[70:71], v[6:7]
	v_mov_b64_e32 v[68:69], v[4:5]
	v_mov_b64_e32 v[66:67], v[2:3]
	v_mov_b64_e32 v[64:65], v[0:1]
	v_mov_b64_e32 v[44:45], v[12:13]
	v_mov_b64_e32 v[42:43], v[10:11]
	v_mov_b64_e32 v[40:41], v[8:9]
	v_mov_b64_e32 v[38:39], v[6:7]
	v_mov_b64_e32 v[36:37], v[4:5]
	v_mov_b64_e32 v[34:35], v[2:3]
	v_mov_b64_e32 v[32:33], v[0:1]
	v_mov_b64_e32 v[60:61], v[12:13]
	v_mov_b64_e32 v[58:59], v[10:11]
	v_mov_b64_e32 v[56:57], v[8:9]
	v_mov_b64_e32 v[54:55], v[6:7]
	v_mov_b64_e32 v[52:53], v[4:5]
	v_mov_b64_e32 v[50:51], v[2:3]
	v_mov_b64_e32 v[48:49], v[0:1]
	v_mov_b64_e32 v[28:29], v[12:13]
	v_mov_b64_e32 v[26:27], v[10:11]
	v_mov_b64_e32 v[24:25], v[8:9]
	v_mov_b64_e32 v[22:23], v[6:7]
	v_mov_b64_e32 v[20:21], v[4:5]
	v_mov_b64_e32 v[18:19], v[2:3]
	v_mov_b64_e32 v[16:17], v[0:1]
	v_readfirstlane_b32 s99, v244
	s_lshr_b32 s99, s99, 8
	s_cmp_eq_u32 s99, 0
	s_cbranch_scc1 .Lpr_mix1e_0
	s_setprio 1
	s_branch .Lpr_mix1e_1
.Lpr_mix1e_0:
	s_setprio 0
.Lpr_mix1e_1:
.LBB0_360:
	s_cmp_lt_i32 s39, 5
	s_cselect_b64 s[6:7], -1, 0
	s_cmp_gt_i32 s39, 4
	s_cselect_b64 s[14:15], -1, 0
	s_mov_b32 s62, 5
	s_and_b64 vcc, exec, s[14:15]
	s_cbranch_vccnz .LBB0_369
	s_lshl_b32 s18, s39, 7
	s_mov_b32 s62, s39
	s_branch .LBB0_363

.LBB0_378:
	v_or_b32_e32 v221, s35, v215
	v_mad_u32_u24 v225, v221, s89, v224
	ds_read_b64_tr_b16 v[226:227], v225 offset:18432
	ds_read_b64_tr_b16 v[228:229], v225 offset:19584
	ds_read_b64_tr_b16 v[230:231], v225 offset:18496
	ds_read_b64_tr_b16 v[232:233], v225 offset:19648
	ds_read_b64_tr_b16 v[234:235], v225 offset:20736
	ds_read_b64_tr_b16 v[236:237], v225 offset:21888
	v_pk_add_f32 v[2:3], v[128:129], v[200:201] op_sel_hi:[1,0] neg_lo:[0,1] neg_hi:[0,1]
	v_pk_add_f32 v[4:5], v[130:131], v[200:201] op_sel_hi:[1,0] neg_lo:[0,1] neg_hi:[0,1]
	v_exp_f32_e32 v204, v2
	v_exp_f32_e32 v205, v3
	v_exp_f32_e32 v206, v4
	v_exp_f32_e32 v207, v5
	v_pk_add_f32 v[4:5], v[132:133], v[200:201] op_sel_hi:[1,0] neg_lo:[0,1] neg_hi:[0,1]
	v_pk_add_f32 v[2:3], v[204:205], 0 op_sel_hi:[1,0]
	v_exp_f32_e32 v208, v4
	v_exp_f32_e32 v209, v5
	v_pk_add_f32 v[4:5], v[134:135], v[200:201] op_sel_hi:[1,0] neg_lo:[0,1] neg_hi:[0,1]
	v_pk_add_f32 v[2:3], v[206:207], v[2:3]
	v_exp_f32_e32 v210, v4
	v_exp_f32_e32 v211, v5
	v_pk_add_f32 v[4:5], v[136:137], v[200:201] op_sel_hi:[1,0] neg_lo:[0,1] neg_hi:[0,1]
	v_pk_add_f32 v[2:3], v[208:209], v[2:3]
	v_exp_f32_e32 v128, v4
	v_exp_f32_e32 v129, v5
	v_pk_add_f32 v[4:5], v[138:139], v[200:201] op_sel_hi:[1,0] neg_lo:[0,1] neg_hi:[0,1]
	v_pk_add_f32 v[2:3], v[210:211], v[2:3]
	v_exp_f32_e32 v130, v4
	v_exp_f32_e32 v131, v5
	v_pk_add_f32 v[4:5], v[140:141], v[200:201] op_sel_hi:[1,0] neg_lo:[0,1] neg_hi:[0,1]
	v_pk_add_f32 v[2:3], v[128:129], v[2:3]
	v_exp_f32_e32 v132, v4
	v_exp_f32_e32 v133, v5
	v_pk_add_f32 v[4:5], v[142:143], v[200:201] op_sel_hi:[1,0] neg_lo:[0,1] neg_hi:[0,1]
	v_pk_add_f32 v[2:3], v[130:131], v[2:3]
	v_exp_f32_e32 v134, v4
	v_exp_f32_e32 v135, v5
	v_pk_add_f32 v[4:5], v[112:113], v[200:201] op_sel_hi:[1,0] neg_lo:[0,1] neg_hi:[0,1]
	v_pk_add_f32 v[2:3], v[132:133], v[2:3]
	v_exp_f32_e32 v10, v4
	v_exp_f32_e32 v11, v5
	v_pk_add_f32 v[4:5], v[114:115], v[200:201] op_sel_hi:[1,0] neg_lo:[0,1] neg_hi:[0,1]
	v_pk_add_f32 v[2:3], v[134:135], v[2:3]
	v_exp_f32_e32 v12, v4
	v_exp_f32_e32 v13, v5
	v_pk_add_f32 v[4:5], v[116:117], v[200:201] op_sel_hi:[1,0] neg_lo:[0,1] neg_hi:[0,1]
	v_pk_add_f32 v[2:3], v[10:11], v[2:3]
	v_exp_f32_e32 v14, v4
	v_exp_f32_e32 v15, v5
	v_pk_add_f32 v[4:5], v[118:119], v[200:201] op_sel_hi:[1,0] neg_lo:[0,1] neg_hi:[0,1]
	v_pk_add_f32 v[2:3], v[12:13], v[2:3]
	v_exp_f32_e32 v112, v4
	v_exp_f32_e32 v113, v5
	v_pk_add_f32 v[2:3], v[14:15], v[2:3]
	v_pk_add_f32 v[80:81], v[80:81], v[202:203] op_sel_hi:[1,0] neg_lo:[0,1] neg_hi:[0,1]
	v_pk_add_f32 v[82:83], v[82:83], v[202:203] op_sel_hi:[1,0] neg_lo:[0,1] neg_hi:[0,1]
	v_pk_add_f32 v[4:5], v[112:113], v[2:3]
	v_pk_add_f32 v[2:3], v[120:121], v[200:201] op_sel_hi:[1,0] neg_lo:[0,1] neg_hi:[0,1]
	s_nop 0
	v_exp_f32_e32 v2, v2
	v_exp_f32_e32 v3, v3
	s_nop 0
	v_pk_add_f32 v[6:7], v[2:3], v[4:5]
	v_pk_add_f32 v[4:5], v[122:123], v[200:201] op_sel_hi:[1,0] neg_lo:[0,1] neg_hi:[0,1]
	v_exp_f32_e32 v122, v80
	v_exp_f32_e32 v4, v4
	v_exp_f32_e32 v5, v5
	v_exp_f32_e32 v123, v81
	v_pk_add_f32 v[8:9], v[4:5], v[6:7]
	v_pk_add_f32 v[6:7], v[124:125], v[200:201] op_sel_hi:[1,0] neg_lo:[0,1] neg_hi:[0,1]
	v_exp_f32_e32 v124, v82
	v_exp_f32_e32 v6, v6
	v_exp_f32_e32 v7, v7
	v_exp_f32_e32 v125, v83
	v_pk_add_f32 v[82:83], v[84:85], v[202:203] op_sel_hi:[1,0] neg_lo:[0,1] neg_hi:[0,1]
	v_pk_add_f32 v[80:81], v[122:123], 0 op_sel_hi:[1,0]
	v_pk_add_f32 v[114:115], v[6:7], v[8:9]
	v_pk_add_f32 v[8:9], v[126:127], v[200:201] op_sel_hi:[1,0] neg_lo:[0,1] neg_hi:[0,1]
	v_exp_f32_e32 v126, v82
	v_exp_f32_e32 v8, v8
	v_exp_f32_e32 v9, v9
	v_exp_f32_e32 v127, v83
	v_pk_add_f32 v[82:83], v[86:87], v[202:203] op_sel_hi:[1,0] neg_lo:[0,1] neg_hi:[0,1]
	v_pk_add_f32 v[80:81], v[124:125], v[80:81]
	v_pk_add_f32 v[114:115], v[8:9], v[114:115]
	v_exp_f32_e32 v136, v82
	v_add_f32_e32 v114, v114, v115
	v_exp_f32_e32 v137, v83
	v_pk_add_f32 v[82:83], v[88:89], v[202:203] op_sel_hi:[1,0] neg_lo:[0,1] neg_hi:[0,1]
	v_add_f32_e32 v216, v216, v114
	v_exp_f32_e32 v114, v82
	v_exp_f32_e32 v115, v83
	v_pk_add_f32 v[82:83], v[90:91], v[202:203] op_sel_hi:[1,0] neg_lo:[0,1] neg_hi:[0,1]
	v_pk_add_f32 v[80:81], v[126:127], v[80:81]
	v_exp_f32_e32 v116, v82
	v_exp_f32_e32 v117, v83
	v_pk_add_f32 v[82:83], v[92:93], v[202:203] op_sel_hi:[1,0] neg_lo:[0,1] neg_hi:[0,1]
	v_pk_add_f32 v[80:81], v[136:137], v[80:81]
	v_exp_f32_e32 v118, v82
	v_exp_f32_e32 v119, v83
	v_pk_add_f32 v[82:83], v[94:95], v[202:203] op_sel_hi:[1,0] neg_lo:[0,1] neg_hi:[0,1]
	v_pk_add_f32 v[80:81], v[114:115], v[80:81]
	v_exp_f32_e32 v120, v82
	v_exp_f32_e32 v121, v83
	v_pk_add_f32 v[82:83], v[96:97], v[202:203] op_sel_hi:[1,0] neg_lo:[0,1] neg_hi:[0,1]
	v_pk_add_f32 v[80:81], v[116:117], v[80:81]
	v_exp_f32_e32 v88, v82
	v_exp_f32_e32 v89, v83
	v_pk_add_f32 v[82:83], v[98:99], v[202:203] op_sel_hi:[1,0] neg_lo:[0,1] neg_hi:[0,1]
	v_pk_add_f32 v[80:81], v[118:119], v[80:81]
	v_exp_f32_e32 v90, v82
	v_exp_f32_e32 v91, v83
	v_pk_add_f32 v[82:83], v[100:101], v[202:203] op_sel_hi:[1,0] neg_lo:[0,1] neg_hi:[0,1]
	v_pk_add_f32 v[80:81], v[120:121], v[80:81]
	v_exp_f32_e32 v92, v82
	v_exp_f32_e32 v93, v83
	v_pk_add_f32 v[82:83], v[102:103], v[202:203] op_sel_hi:[1,0] neg_lo:[0,1] neg_hi:[0,1]
	v_pk_add_f32 v[80:81], v[88:89], v[80:81]
	v_exp_f32_e32 v94, v82
	v_exp_f32_e32 v95, v83
	v_pk_add_f32 v[80:81], v[90:91], v[80:81]
	s_nop 0
	v_pk_add_f32 v[80:81], v[92:93], v[80:81]
	s_nop 0
	v_pk_add_f32 v[82:83], v[94:95], v[80:81]
	v_pk_add_f32 v[80:81], v[104:105], v[202:203] op_sel_hi:[1,0] neg_lo:[0,1] neg_hi:[0,1]
	v_or_b32_e32 v104, s35, v215
	v_exp_f32_e32 v80, v80
	v_exp_f32_e32 v81, v81
	s_nop 0
	v_pk_add_f32 v[84:85], v[80:81], v[82:83]
	v_pk_add_f32 v[82:83], v[106:107], v[202:203] op_sel_hi:[1,0] neg_lo:[0,1] neg_hi:[0,1]
	s_nop 0
	v_exp_f32_e32 v82, v82
	v_exp_f32_e32 v83, v83
	s_nop 0
	v_pk_add_f32 v[86:87], v[82:83], v[84:85]
	v_pk_add_f32 v[84:85], v[108:109], v[202:203] op_sel_hi:[1,0] neg_lo:[0,1] neg_hi:[0,1]
	v_exp_f32_e32 v84, v84
	v_exp_f32_e32 v85, v85
	s_nop 0
	v_pk_add_f32 v[96:97], v[84:85], v[86:87]
	v_pk_add_f32 v[86:87], v[110:111], v[202:203] op_sel_hi:[1,0] neg_lo:[0,1] neg_hi:[0,1]
	s_nop 0
	v_exp_f32_e32 v86, v86
	v_exp_f32_e32 v87, v87
	s_nop 0
	v_pk_add_f32 v[96:97], v[86:87], v[96:97]
	s_nop 0
	v_add_f32_e32 v96, v96, v97
	v_add_f32_e32 v212, v212, v96
	v_cvt_pk_bf16_f32 v96, v204, v205
	v_cvt_pk_bf16_f32 v97, v206, v207
	v_cvt_pk_bf16_f32 v98, v208, v209
	v_cvt_pk_bf16_f32 v99, v210, v211
	v_cvt_pk_bf16_f32 v100, v122, v123
	v_cvt_pk_bf16_f32 v101, v124, v125
	v_cvt_pk_bf16_f32 v102, v126, v127
	v_cvt_pk_bf16_f32 v103, v136, v137
	s_cmp_eq_u32 s99, 0
	s_cbranch_scc1 .Lpr_mix1a_0
	s_setprio 3
	s_branch .Lpr_mix1a_1

.Lpr_mix1a_1:
	s_waitcnt lgkmcnt(4)
	v_mfma_f32_32x32x16_bf16 v[64:79], v[226:229], v[96:99], v[64:79]
	v_mfma_f32_32x32x16_bf16 v[32:47], v[226:229], v[100:103], v[32:47]
	ds_read_b64_tr_b16 v[226:227], v225 offset:20800
	ds_read_b64_tr_b16 v[228:229], v225 offset:21952
	s_waitcnt lgkmcnt(4)
	v_mfma_f32_32x32x16_bf16 v[48:63], v[230:233], v[96:99], v[48:63]
	v_cvt_pk_bf16_f32 v96, v128, v129
	v_cvt_pk_bf16_f32 v97, v130, v131
	v_cvt_pk_bf16_f32 v98, v132, v133
	v_cvt_pk_bf16_f32 v99, v134, v135
	v_mfma_f32_32x32x16_bf16 v[16:31], v[230:233], v[100:103], v[16:31]
	v_cvt_pk_bf16_f32 v100, v114, v115
	v_cvt_pk_bf16_f32 v101, v116, v117
	v_cvt_pk_bf16_f32 v102, v118, v119
	v_cvt_pk_bf16_f32 v103, v120, v121
	ds_read_b64_tr_b16 v[230:231], v225 offset:23040
	ds_read_b64_tr_b16 v[232:233], v225 offset:24192
	s_waitcnt lgkmcnt(4)
	v_mfma_f32_32x32x16_bf16 v[64:79], v[234:237], v[96:99], v[64:79]
	v_mfma_f32_32x32x16_bf16 v[32:47], v[234:237], v[100:103], v[32:47]
	ds_read_b64_tr_b16 v[234:235], v225 offset:23104
	ds_read_b64_tr_b16 v[236:237], v225 offset:24256
	s_waitcnt lgkmcnt(4)
	v_mfma_f32_32x32x16_bf16 v[48:63], v[226:229], v[96:99], v[48:63]
	v_cvt_pk_bf16_f32 v10, v10, v11
	v_cvt_pk_bf16_f32 v11, v12, v13
	v_cvt_pk_bf16_f32 v12, v14, v15
	v_cvt_pk_bf16_f32 v13, v112, v113
	v_mfma_f32_32x32x16_bf16 v[16:31], v[226:229], v[100:103], v[16:31]
	v_cvt_pk_bf16_f32 v88, v88, v89
	v_cvt_pk_bf16_f32 v89, v90, v91
	v_cvt_pk_bf16_f32 v90, v92, v93
	v_cvt_pk_bf16_f32 v91, v94, v95
	ds_read_b64_tr_b16 v[226:227], v225 offset:25344
	ds_read_b64_tr_b16 v[228:229], v225 offset:26496
	s_waitcnt lgkmcnt(4)
	v_mfma_f32_32x32x16_bf16 v[64:79], v[230:233], v[10:13], v[64:79]
	v_mfma_f32_32x32x16_bf16 v[32:47], v[230:233], v[88:91], v[32:47]
	ds_read_b64_tr_b16 v[230:231], v225 offset:25408
	ds_read_b64_tr_b16 v[232:233], v225 offset:26560
	s_waitcnt lgkmcnt(4)
	v_mfma_f32_32x32x16_bf16 v[48:63], v[234:237], v[10:13], v[48:63]
	v_cvt_pk_bf16_f32 v2, v2, v3
	v_cvt_pk_bf16_f32 v3, v4, v5
	v_cvt_pk_bf16_f32 v4, v6, v7
	v_cvt_pk_bf16_f32 v5, v8, v9
	v_mfma_f32_32x32x16_bf16 v[16:31], v[234:237], v[88:91], v[16:31]
	v_cvt_pk_bf16_f32 v6, v80, v81
	v_cvt_pk_bf16_f32 v7, v82, v83
	v_cvt_pk_bf16_f32 v8, v84, v85
	v_cvt_pk_bf16_f32 v9, v86, v87
	s_waitcnt lgkmcnt(2)
	v_mfma_f32_32x32x16_bf16 v[64:79], v[226:229], v[2:5], v[64:79]
	v_mfma_f32_32x32x16_bf16 v[32:47], v[226:229], v[6:9], v[32:47]
	s_waitcnt lgkmcnt(0)
	v_mfma_f32_32x32x16_bf16 v[48:63], v[230:233], v[2:5], v[48:63]
	v_mfma_f32_32x32x16_bf16 v[16:31], v[230:233], v[6:9], v[16:31]
	s_cmp_eq_u32 s99, 0
	s_cbranch_scc1 .Lpr_mix1b_0
	s_setprio 1
	s_branch .Lpr_mix1b_1

.Lpr_mix1b_1:
.LBB0_379:
	s_xor_b64 s[6:7], s[20:21], -1
	s_mov_b32 s35, 64
	s_mov_b64 s[20:21], 0
	s_and_b64 vcc, exec, s[6:7]
	s_cbranch_vccnz .LBB0_391

.LBB0_382:
	s_andn2_b64 vcc, exec, s[6:7]
	s_cbranch_vccnz .LBB0_379
	v_or_b32_e32 v2, s35, v203
	v_mad_u32_u24 v14, v2, s89, v0
	s_cmp_eq_u32 s99, 0
	s_cbranch_scc1 .Lpr_mix1q_0
	s_setprio 3
	s_branch .Lpr_mix1q_1

.Lpr_mix1q_1:
	ds_read_b128 v[2:5], v14
	ds_read_b128 v[6:9], v14 offset:32
	ds_read_b128 v[10:13], v14 offset:64
	ds_read_b128 v[96:99], v14 offset:96
	s_cmp_lt_i32 s8, s48
	s_waitcnt vmcnt(7) lgkmcnt(3)
	v_mfma_f32_32x32x16_bf16 v[128:143], v[2:5], v[144:147], 0
	s_cselect_b64 s[6:7], -1, 0
	s_cmp_gt_i32 s8, s49
	s_cselect_b64 s[50:51], -1, 0
	s_or_b64 s[6:7], s[6:7], s[50:51]
	s_and_b64 s[50:51], s[16:17], s[6:7]
	s_andn2_b64 vcc, exec, s[50:51]
	s_waitcnt vmcnt(3)
	v_mfma_f32_32x32x16_bf16 v[80:95], v[2:5], v[160:163], 0
	s_waitcnt lgkmcnt(2)
	v_mfma_f32_32x32x16_bf16 v[128:143], v[6:9], v[148:151], v[128:143]
	s_waitcnt vmcnt(2)
	v_mfma_f32_32x32x16_bf16 v[80:95], v[6:9], v[164:167], v[80:95]
	s_waitcnt lgkmcnt(1)
	v_mfma_f32_32x32x16_bf16 v[128:143], v[10:13], v[152:155], v[128:143]
	s_waitcnt vmcnt(1)
	v_mfma_f32_32x32x16_bf16 v[80:95], v[10:13], v[168:171], v[80:95]
	ds_read_b128 v[2:5], v14 offset:4608
	ds_read_b128 v[6:9], v14 offset:4640
	ds_read_b128 v[10:13], v14 offset:4672
	ds_read_b128 v[204:207], v14 offset:4704
	s_waitcnt lgkmcnt(4)
	v_mfma_f32_32x32x16_bf16 v[128:143], v[96:99], v[156:159], v[128:143]
	s_waitcnt vmcnt(0)
	v_mfma_f32_32x32x16_bf16 v[80:95], v[96:99], v[172:175], v[80:95]
	s_waitcnt lgkmcnt(3)
	v_mfma_f32_32x32x16_bf16 v[112:127], v[2:5], v[144:147], 0
	v_mfma_f32_32x32x16_bf16 v[96:111], v[2:5], v[160:163], 0
	v_add_u32_e32 v2, s8, v217
	v_cndmask_b32_e64 v3, 0, 1, s[50:51]
	v_cmp_ne_u32_e64 s[6:7], 1, v3
	s_waitcnt lgkmcnt(2)
	v_mfma_f32_32x32x16_bf16 v[112:127], v[6:9], v[148:151], v[112:127]
	v_mfma_f32_32x32x16_bf16 v[96:111], v[6:9], v[164:167], v[96:111]
	s_waitcnt lgkmcnt(1)
	v_mfma_f32_32x32x16_bf16 v[112:127], v[10:13], v[152:155], v[112:127]
	v_mfma_f32_32x32x16_bf16 v[96:111], v[10:13], v[168:171], v[96:111]
	v_subrev_u32_e32 v10, s45, v2
	v_cmp_gt_u32_e64 s[8:9], s33, v10
	v_add_u32_e32 v15, 0xffffff02, v10
	v_add_u32_e32 v13, 0xffffff07, v10
	v_add_u32_e32 v11, 0xffffff08, v10
	v_add_u32_e32 v8, 0xffffff09, v10
	v_add_u32_e32 v6, 0xffffff0a, v10
	s_waitcnt lgkmcnt(0)
	v_mfma_f32_32x32x16_bf16 v[112:127], v[204:207], v[156:159], v[112:127]
	v_add_u32_e32 v14, 0xffffff0f, v10
	v_add_u32_e32 v12, 0xffffff10, v10
	v_add_u32_e32 v9, 0xffffff11, v10
	v_add_u32_e32 v7, 0xffffff12, v10
	v_add_u32_e32 v5, 0xffffff17, v10
	v_add_u32_e32 v4, 0xffffff18, v10
	v_add_u32_e32 v3, 0xffffff19, v10
	v_mfma_f32_32x32x16_bf16 v[96:111], v[204:207], v[172:175], v[96:111]
	s_cmp_eq_u32 s99, 0
	s_cbranch_scc1 .Lpr_mix1r_0
	s_setprio 1
	s_branch .Lpr_mix1r_1

.Lpr_mix1r_1:
	v_add_u32_e32 v205, 0xffffff00, v10
	v_add_u32_e32 v204, 0xffffff01, v10
	v_add_u32_e32 v2, 0xffffff1a, v10
	s_cbranch_vccnz .LBB0_385
	v_cmp_lt_u32_e32 vcc, s67, v205
	v_add_u32_e32 v206, 0xffffff1f, v10
	v_cndmask_b32_e64 v128, v243, v128, s[8:9]
	v_cndmask_b32_e32 v129, v243, v129, vcc
	v_cmp_lt_u32_e32 vcc, s67, v204
	s_nop 1
	v_cndmask_b32_e32 v130, v243, v130, vcc
	v_cmp_lt_u32_e32 vcc, s67, v15
	s_nop 1
	v_cndmask_b32_e32 v131, v243, v131, vcc
	v_cmp_lt_u32_e32 vcc, s67, v13
	s_nop 1
	v_cndmask_b32_e32 v132, v243, v132, vcc
	v_cmp_lt_u32_e32 vcc, s67, v11
	s_nop 1
	v_cndmask_b32_e32 v133, v243, v133, vcc
	v_cmp_lt_u32_e32 vcc, s67, v8
	s_nop 1
	v_cndmask_b32_e32 v134, v243, v134, vcc
	v_cmp_lt_u32_e32 vcc, s67, v6
	s_nop 1
	v_cndmask_b32_e32 v135, v243, v135, vcc
	v_cmp_lt_u32_e32 vcc, s67, v14
	s_nop 1
	v_cndmask_b32_e32 v136, v243, v136, vcc
	v_cmp_lt_u32_e32 vcc, s67, v12
	s_nop 1
	v_cndmask_b32_e32 v137, v243, v137, vcc
	v_cmp_lt_u32_e32 vcc, s67, v9
	s_nop 1
	v_cndmask_b32_e32 v138, v243, v138, vcc
	v_cmp_lt_u32_e32 vcc, s67, v7
	s_nop 1
	v_cndmask_b32_e32 v139, v243, v139, vcc
	v_cmp_lt_u32_e32 vcc, s67, v5
	s_nop 1
	v_cndmask_b32_e32 v140, v243, v140, vcc
	v_cmp_lt_u32_e32 vcc, s67, v4
	s_nop 1
	v_cndmask_b32_e32 v141, v243, v141, vcc
	v_cmp_lt_u32_e32 vcc, s67, v3
	s_nop 1
	v_cndmask_b32_e32 v142, v243, v142, vcc
	v_cmp_lt_u32_e32 vcc, s67, v2
	s_nop 1
	v_cndmask_b32_e32 v143, v243, v143, vcc
	v_cmp_lt_u32_e32 vcc, s67, v206
	v_add_u32_e32 v206, 0xffffff20, v10
	s_nop 0
	v_cndmask_b32_e32 v112, v243, v112, vcc
	v_cmp_lt_u32_e32 vcc, s67, v206
	v_add_u32_e32 v206, 0xffffff21, v10
	s_nop 0
	v_cndmask_b32_e32 v113, v243, v113, vcc
	v_cmp_lt_u32_e32 vcc, s67, v206
	v_add_u32_e32 v206, 0xffffff22, v10
	s_nop 0
	v_cndmask_b32_e32 v114, v243, v114, vcc
	v_cmp_lt_u32_e32 vcc, s67, v206
	v_add_u32_e32 v206, 0xffffff27, v10
	s_nop 0
	v_cndmask_b32_e32 v115, v243, v115, vcc
	v_cmp_lt_u32_e32 vcc, s67, v206
	v_add_u32_e32 v206, 0xffffff28, v10
	s_nop 0
	v_cndmask_b32_e32 v116, v243, v116, vcc
	v_cmp_lt_u32_e32 vcc, s67, v206
	v_add_u32_e32 v206, 0xffffff29, v10
	s_nop 0
	v_cndmask_b32_e32 v117, v243, v117, vcc
	v_cmp_lt_u32_e32 vcc, s67, v206
	v_add_u32_e32 v206, 0xffffff2a, v10
	s_nop 0
	v_cndmask_b32_e32 v118, v243, v118, vcc
	v_cmp_lt_u32_e32 vcc, s67, v206
	v_add_u32_e32 v206, 0xffffff2f, v10
	s_nop 0
	v_cndmask_b32_e32 v119, v243, v119, vcc
	v_cmp_lt_u32_e32 vcc, s67, v206
	v_add_u32_e32 v206, 0xffffff30, v10
	s_nop 0
	v_cndmask_b32_e32 v120, v243, v120, vcc
	v_cmp_lt_u32_e32 vcc, s67, v206
	v_add_u32_e32 v206, 0xffffff31, v10
	s_nop 0
	v_cndmask_b32_e32 v121, v243, v121, vcc
	v_cmp_lt_u32_e32 vcc, s67, v206
	v_add_u32_e32 v206, 0xffffff32, v10
	s_nop 0
	v_cndmask_b32_e32 v122, v243, v122, vcc
	v_cmp_lt_u32_e32 vcc, s67, v206
	v_add_u32_e32 v206, 0xffffff37, v10
	s_nop 0
	v_cndmask_b32_e32 v123, v243, v123, vcc
	v_cmp_lt_u32_e32 vcc, s67, v206
	v_add_u32_e32 v206, 0xffffff38, v10
	s_nop 0
	v_cndmask_b32_e32 v124, v243, v124, vcc
	v_cmp_lt_u32_e32 vcc, s67, v206
	v_add_u32_e32 v206, 0xffffff39, v10
	s_nop 0
	v_cndmask_b32_e32 v125, v243, v125, vcc
	v_cmp_lt_u32_e32 vcc, s67, v206
	v_add_u32_e32 v206, 0xffffff3a, v10
	s_nop 0
	v_cndmask_b32_e32 v126, v243, v126, vcc
	v_cmp_lt_u32_e32 vcc, s67, v206
	s_nop 1
	v_cndmask_b32_e32 v127, v243, v127, vcc
